# scan chunk epilogue: the bonus LDS read is issued with the y read and retired by the same wait (one exposed LDS round trip instead of two per chunk)
# baseline (speedup 1.0000x reference)
; DI unsigned pack2(float a, float b) { f32x2 v = {a, b}; bfx2 r = __builtin_convertvector(v, bfx2); return __builtin_bit_cast(unsigned, r); }
; DI void scan_item(const Params& p, int b, int h, int half, char* smem, unsigned* pgen, unsigned kp) {
;     ...
;     {
;       const int t = c * SC + ls;
;       const size_t m = (size_t)b * T + t;
;       const int j2 = (tid & 15) * 2;
;       const f32x2 y2 = *(const f32x2*)(Yl + ls * 32 + j2);
;       *(unsigned*)(mix + m * 1024 + 512 + h * 64 + 32 * half + j2) = pack2(y2.x, y2.y);
;       if (half == 0 && (tid & 15) == 0) ((float*)(p.ws + OFF_BON))[m * 8 + h] = BON[ls];
;     }
.LBB0_705:
	s_waitcnt lgkmcnt(0)
	s_barrier
	ds_read_b64 v[36:37], v215 offset:24576
	ds_read_b32 v154, v171 offset:28672
	s_lshl_b32 s25, s25, 4
	v_add_u32_e32 v0, s25, v170
	v_lshl_add_u64 v[34:35], s[6:7], 0, v[0:1]
	s_waitcnt lgkmcnt(0)
	v_cvt_pk_f16_f32 v38, v36, v37
	v_lshlrev_b64 v[36:37], 11, v[34:35]
	v_lshl_add_u64 v[36:37], v[142:143], 0, v[36:37]
	global_store_dword v[36:37], v38, off offset:1024
	s_and_saveexec_b64 s[18:19], s[22:23]
	s_cbranch_execz .LBB0_707
	v_lshlrev_b64 v[34:35], 5, v[34:35]
	v_lshl_add_u64 v[34:35], s[10:11], 0, v[34:35]
	global_store_dword v[34:35], v154, off

; DI unsigned pack2(float a, float b) { f32x2 v = {a, b}; bfx2 r = __builtin_convertvector(v, bfx2); return __builtin_bit_cast(unsigned, r); }
; DI void scan_item(const Params& p, int b, int h, int half, char* smem, unsigned* pgen, unsigned kp) {
;     ...
;     {
;       const int t = c * SC + ls;
;       const size_t m = (size_t)b * T + t;
;       const int j2 = (tid & 15) * 2;
;       const f32x2 y2 = *(const f32x2*)(Yl + ls * 32 + j2);
;       *(unsigned*)(mix + m * 1024 + 512 + h * 64 + 32 * half + j2) = pack2(y2.x, y2.y);
;       if (half == 0 && (tid & 15) == 0) ((float*)(p.ws + OFF_BON))[m * 8 + h] = BON[ls];
;     }
.LBB0_715:
	s_waitcnt lgkmcnt(0)
	s_barrier
	ds_read_b64 v[36:37], v215 offset:24576
	ds_read_b32 v154, v171 offset:28672
	v_add_u32_e32 v0, s25, v178
	v_lshl_add_u64 v[34:35], s[6:7], 0, v[0:1]
	s_waitcnt lgkmcnt(0)
	v_cvt_pk_f16_f32 v0, v36, v37
	v_lshlrev_b64 v[36:37], 11, v[34:35]
	v_lshl_add_u64 v[36:37], v[142:143], 0, v[36:37]
	global_store_dword v[36:37], v0, off offset:1024
	s_and_saveexec_b64 s[4:5], s[22:23]
	s_cbranch_execz .LBB0_686
	v_lshlrev_b64 v[34:35], 5, v[34:35]
	v_lshl_add_u64 v[34:35], s[10:11], 0, v[34:35]
	global_store_dword v[34:35], v154, off
	s_branch .LBB0_686
